# attention work stealing: peek the seven other queue counters in one round trip and skip ticket atomics on queues already empty
# speedup vs baseline: 1.0025x; 1.0025x over previous
.LBB0_321:
	s_or_b64 exec, exec, s[8:9]
	s_waitcnt vmcnt(4)
	v_readfirstlane_b32 s8, v2
	s_mov_b64 s[52:53], -1
	v_mov_b32_e32 v2, s79
	v_add_u32_e32 v0, s8, v0
	v_cmp_lt_u32_e32 vcc, s87, v0
	s_and_saveexec_b64 s[8:9], vcc
	s_cbranch_execz .LBB0_349
	global_load_dword v230, v1, s[14:15] sc1
	global_load_dword v231, v1, s[16:17] sc1
	global_load_dword v232, v1, s[18:19] sc1
	global_load_dword v233, v1, s[22:23] sc1
	global_load_dword v234, v1, s[24:25] sc1
	global_load_dword v235, v1, s[36:37] sc1
	global_load_dword v236, v1, s[38:39] sc1
	s_waitcnt vmcnt(0)
	s_mov_b64 s[54:55], exec
	v_mbcnt_lo_u32_b32 v0, s54, 0
	v_mbcnt_hi_u32_b32 v0, s55, v0
	v_cmp_eq_u32_e32 vcc, 0, v0
	s_and_saveexec_b64 s[52:53], vcc
	s_cbranch_execz .LBB0_324
	s_bcnt1_i32_b64 s10, s[54:55]
	v_mov_b32_e32 v2, s10
	v_cmp_gt_u32_e32 vcc, 0x80, v230
	s_cbranch_vccz .Lattn_pk_skip_0
	global_atomic_add v2, v1, v2, s[14:15] sc0
	s_branch .Lattn_pk_cont_0
.Lattn_pk_skip_0:
	v_mov_b32_e32 v2, v230
.Lattn_pk_cont_0:
.LBB0_324:
	s_or_b64 exec, exec, s[52:53]
	s_waitcnt vmcnt(0)
	v_readfirstlane_b32 s10, v2
	s_mov_b64 s[54:55], -1
	v_mov_b32_e32 v2, s80
	v_add_u32_e32 v0, s10, v0
	v_cmp_lt_u32_e32 vcc, s87, v0
	s_and_saveexec_b64 s[52:53], vcc
	s_cbranch_execz .LBB0_348
	s_mov_b64 s[56:57], exec
	v_mbcnt_lo_u32_b32 v0, s56, 0
	v_mbcnt_hi_u32_b32 v0, s57, v0
	v_cmp_eq_u32_e32 vcc, 0, v0
	s_and_saveexec_b64 s[54:55], vcc
	s_cbranch_execz .LBB0_327
	s_bcnt1_i32_b64 s10, s[56:57]
	v_mov_b32_e32 v2, s10
	v_cmp_gt_u32_e32 vcc, 0x80, v231
	s_cbranch_vccz .Lattn_pk_skip_1
	global_atomic_add v2, v1, v2, s[16:17] sc0
	s_branch .Lattn_pk_cont_1
.Lattn_pk_skip_1:
	v_mov_b32_e32 v2, v231
.Lattn_pk_cont_1:
.LBB0_327:
	s_or_b64 exec, exec, s[54:55]
	s_waitcnt vmcnt(0)
	v_readfirstlane_b32 s10, v2
	s_mov_b64 s[56:57], -1
	v_mov_b32_e32 v2, s81
	v_add_u32_e32 v0, s10, v0
	v_cmp_lt_u32_e32 vcc, s87, v0
	s_and_saveexec_b64 s[54:55], vcc
	s_cbranch_execz .LBB0_347
	s_mov_b64 s[58:59], exec
	v_mbcnt_lo_u32_b32 v0, s58, 0
	v_mbcnt_hi_u32_b32 v0, s59, v0
	v_cmp_eq_u32_e32 vcc, 0, v0
	s_and_saveexec_b64 s[56:57], vcc
	s_cbranch_execz .LBB0_330
	s_bcnt1_i32_b64 s10, s[58:59]
	v_mov_b32_e32 v2, s10
	v_cmp_gt_u32_e32 vcc, 0x80, v232
	s_cbranch_vccz .Lattn_pk_skip_2
	global_atomic_add v2, v1, v2, s[18:19] sc0
	s_branch .Lattn_pk_cont_2
.Lattn_pk_skip_2:
	v_mov_b32_e32 v2, v232
.Lattn_pk_cont_2:
.LBB0_330:
	s_or_b64 exec, exec, s[56:57]
	s_waitcnt vmcnt(0)
	v_readfirstlane_b32 s10, v2
	s_mov_b64 s[58:59], -1
	v_mov_b32_e32 v2, s82
	v_add_u32_e32 v0, s10, v0
	v_cmp_lt_u32_e32 vcc, s87, v0
	s_and_saveexec_b64 s[56:57], vcc
	s_cbranch_execz .LBB0_346
	s_mov_b64 s[60:61], exec
	v_mbcnt_lo_u32_b32 v0, s60, 0
	v_mbcnt_hi_u32_b32 v0, s61, v0
	v_cmp_eq_u32_e32 vcc, 0, v0
	s_and_saveexec_b64 s[58:59], vcc
	s_cbranch_execz .LBB0_333
	s_bcnt1_i32_b64 s10, s[60:61]
	v_mov_b32_e32 v2, s10
	v_cmp_gt_u32_e32 vcc, 0x80, v233
	s_cbranch_vccz .Lattn_pk_skip_3
	global_atomic_add v2, v1, v2, s[22:23] sc0
	s_branch .Lattn_pk_cont_3
.Lattn_pk_skip_3:
	v_mov_b32_e32 v2, v233
.Lattn_pk_cont_3:
.LBB0_333:
	s_or_b64 exec, exec, s[58:59]
	s_waitcnt vmcnt(0)
	v_readfirstlane_b32 s10, v2
	s_mov_b64 s[60:61], -1
	v_mov_b32_e32 v2, s83
	v_add_u32_e32 v0, s10, v0
	v_cmp_lt_u32_e32 vcc, s87, v0
	s_and_saveexec_b64 s[58:59], vcc
	s_cbranch_execz .LBB0_345
	s_mov_b64 s[62:63], exec
	v_mbcnt_lo_u32_b32 v0, s62, 0
	v_mbcnt_hi_u32_b32 v0, s63, v0
	v_cmp_eq_u32_e32 vcc, 0, v0
	s_and_saveexec_b64 s[60:61], vcc
	s_cbranch_execz .LBB0_336
	s_bcnt1_i32_b64 s10, s[62:63]
	v_mov_b32_e32 v2, s10
	v_cmp_gt_u32_e32 vcc, 0x80, v234
	s_cbranch_vccz .Lattn_pk_skip_4
	global_atomic_add v2, v1, v2, s[24:25] sc0
	s_branch .Lattn_pk_cont_4
.Lattn_pk_skip_4:
	v_mov_b32_e32 v2, v234
.Lattn_pk_cont_4:
.LBB0_336:
	s_or_b64 exec, exec, s[60:61]
	s_waitcnt vmcnt(0)
	v_readfirstlane_b32 s10, v2
	s_mov_b64 s[62:63], -1
	v_mov_b32_e32 v2, s84
	v_add_u32_e32 v0, s10, v0
	v_cmp_lt_u32_e32 vcc, s87, v0
	s_and_saveexec_b64 s[60:61], vcc
	s_cbranch_execz .LBB0_344
	s_mov_b64 s[64:65], exec
	v_mbcnt_lo_u32_b32 v0, s64, 0
	v_mbcnt_hi_u32_b32 v0, s65, v0
	v_cmp_eq_u32_e32 vcc, 0, v0
	s_and_saveexec_b64 s[62:63], vcc
	s_cbranch_execz .LBB0_339
	s_bcnt1_i32_b64 s10, s[64:65]
	v_mov_b32_e32 v2, s10
	v_cmp_gt_u32_e32 vcc, 0x80, v235
	s_cbranch_vccz .Lattn_pk_skip_5
	global_atomic_add v2, v1, v2, s[36:37] sc0
	s_branch .Lattn_pk_cont_5
.Lattn_pk_skip_5:
	v_mov_b32_e32 v2, v235
.Lattn_pk_cont_5:
.LBB0_339:
	s_or_b64 exec, exec, s[62:63]
	s_waitcnt vmcnt(0)
	v_readfirstlane_b32 s10, v2
	s_mov_b64 s[64:65], -1
	v_mov_b32_e32 v2, s85
	v_add_u32_e32 v0, s10, v0
	v_cmp_lt_u32_e32 vcc, s87, v0
	s_and_saveexec_b64 s[62:63], vcc
	s_cbranch_execz .LBB0_343
	s_mov_b64 s[66:67], exec
	v_mbcnt_lo_u32_b32 v0, s66, 0
	v_mbcnt_hi_u32_b32 v0, s67, v0
	v_cmp_eq_u32_e32 vcc, 0, v0
	s_and_saveexec_b64 s[64:65], vcc
	s_cbranch_execz .LBB0_342
	s_bcnt1_i32_b64 s10, s[66:67]
	v_mov_b32_e32 v2, s10
	v_cmp_gt_u32_e32 vcc, 0x80, v236
	s_cbranch_vccz .Lattn_pk_skip_6
	global_atomic_add v2, v1, v2, s[38:39] sc0
	s_branch .Lattn_pk_cont_6
.Lattn_pk_skip_6:
	v_mov_b32_e32 v2, v236
.Lattn_pk_cont_6:
.LBB0_342:
	s_or_b64 exec, exec, s[64:65]
	s_waitcnt vmcnt(0)
	v_readfirstlane_b32 s10, v2
	v_mov_b32_e32 v2, s86
	s_nop 0
	v_add_u32_e32 v0, s10, v0
	v_cmp_gt_u32_e32 vcc, s90, v0
	s_orn2_b64 s[64:65], vcc, exec
